# P5 tiles after the first come from a device-wide counter (next index fetched by thread 0 at tile start, broadcast through one LDS word), so late arrivals at the P4->P5 hand-off take fewer tiles
# speedup vs baseline: 1.0055x; 1.0055x over previous
.LBB0_3:
	s_or_b64 exec, exec, s[2:3]
	v_cmp_eq_u32_e32 vcc, 0, v0
	s_and_saveexec_b64 s[2:3], vcc
	s_cbranch_execz .Lq5_init_done
	v_mov_b32_e32 v4, s94
	v_mov_b32_e32 v5, s95
	v_add_co_u32_e32 v4, vcc, 0x3020, v4
	s_nop 1
	v_addc_co_u32_e32 v5, vcc, 0, v5, vcc
	v_mov_b32_e32 v6, 0x100
	global_atomic_swap v[4:5], v6, off

.LBB0_342:
	s_and_saveexec_b64 s[100:101], s[2:3]
	s_cbranch_execz .Lq5_nofetch
	s_add_u32 s0, s11, 0x1020
	s_addc_u32 s1, s33, 0
	global_atomic_add v250, v131, v153, s[0:1] sc0
.Lq5_nofetch:
	s_or_b64 exec, exec, s[100:101]
	s_mul_hi_i32 s0, s54, 0x2e8ba2e9
	s_lshr_b32 s1, s0, 31
	s_ashr_i32 s0, s0, 2
	s_add_i32 s34, s0, s1
	s_cmp_lg_u32 s54, s10
	s_cbranch_scc1 .LBB0_354
	s_and_saveexec_b64 s[36:37], s[2:3]
	s_cbranch_execz .LBB0_353
	s_lshl_b32 s0, s34, 4
	s_ashr_i32 s1, s0, 31
	s_lshl_b64 s[0:1], s[0:1], 2
	s_add_u32 s38, s11, s0
	s_addc_u32 s39, s33, s1
	s_mov_b32 s35, 0x400001
	s_branch .LBB0_346

.Lp5_nosig:
	s_mov_b32 s99, s34
	s_and_saveexec_b64 s[100:101], s[2:3]
	s_cbranch_execz .Lq5_nowrite
	v_mov_b32_e32 v251, 0x20600
	ds_write_b32 v251, v250
.Lq5_nowrite:
	s_or_b64 exec, exec, s[100:101]
	s_waitcnt lgkmcnt(0)
	s_barrier
	v_mov_b32_e32 v251, 0x20600
	ds_read_b32 v251, v251
	s_waitcnt lgkmcnt(0)
	v_readfirstlane_b32 s54, v251
	s_nop 3
	s_cmpk_gt_i32 s54, 0x57f
	s_cselect_b64 s[38:39], -1, 0
	s_cmpk_lt_i32 s54, 0x580
	s_cselect_b64 s[0:1], -1, 0
	s_and_b64 s[0:1], s[2:3], s[0:1]
	s_and_saveexec_b64 s[40:41], s[0:1]
	s_cbranch_execz .LBB0_341
	s_mul_hi_i32 s0, s54, 0x2e8ba2e9
	s_lshr_b32 s1, s0, 31
	s_lshr_b32 s0, s0, 2
	s_add_i32 s0, s0, s1
	s_lshl_b32 s0, s0, 4
	s_ashr_i32 s1, s0, 31
	s_lshl_b64 s[0:1], s[0:1], 2
	s_add_u32 s46, s11, s0
	s_addc_u32 s47, s33, s1
	s_mov_b32 s35, 0x400001
	s_branch .LBB0_365
